# rebalance: ffn2 gate conversion moved from gate/up-1 tail to input-projection tail
# speedup vs baseline: 1.0124x; 1.0079x over previous
; #define LAS __attribute__((address_space(3)))
; __device__ __forceinline__ unsigned pk2(float lo, float hi) { f32x2 f = {lo, hi}; bf16x2_t b = __builtin_convertvector(f, bf16x2_t); return __builtin_bit_cast(unsigned, b); }
; template <int MAP, bool HASG, bool PERMW>
; __device__ __forceinline__ void tr_store(int K, int N, bf16_t* WT, LAS float* scr, int item, int lane, const float* gk) {
;     ...
;     asm volatile("s_waitcnt lgkmcnt(0)" ::: "memory");
;     const int c = lane & 7;
;     f32x4 g0 = {1.f, 1.f, 1.f, 1.f}, g1 = {1.f, 1.f, 1.f, 1.f};
;     if (HASG) { g0 = *(const f32x4*)(gk + k0 + 8 * c); g1 = *(const f32x4*)(gk + k0 + 8 * c + 4); }
; #pragma unroll
;     for (int j = 0; j < 4; ++j) { const int n = (lane >> 3) + 8 * j; const LAS float* s = scr + (8 * c) * 33 + n;
;         u32x4 o; o.x = pk2(s[0 * 33] * g0[0], s[1 * 33] * g0[1]); o.y = pk2(s[2 * 33] * g0[2], s[3 * 33] * g0[3]); o.z = pk2(s[4 * 33] * g1[0], s[5 * 33] * g1[1]); o.w = pk2(s[6 * 33] * g1[2], s[7 * 33] * g1[3]);
;         const int wr_ = rowmap<MAP>(n0 + n), slot_ = PERMW ? ((wr_ & ~31) + invperm32(wr_ & 31)) : wr_;
;         *(u32x4*)((char*)WT + tiled_off(slot_, k0 + 8 * c, K / 64)) = o; }
;     asm volatile("s_waitcnt lgkmcnt(0)" ::: "memory");
; template <int MAP, bool HASG = false, bool PERMW = false>
; __device__ __forceinline__ void transpose_mat(const float* W, int K, int N, bf16_t* WT, LAS float* scr, int gw, int ngw, int lane, const float* gk = nullptr) {
;     ...
;         for (int i = 0; i < 32; ++i) { const int kk = 2 * i + (lane >> 5); scr[kk * 33 + (lane & 31)] = wv[i]; }
.Ltc1a_lastB:
	s_waitcnt vmcnt(0)
	ds_write_b32 v4, v88
	ds_write_b32 v4, v89 offset:264
	ds_write_b32 v4, v90 offset:528
	ds_write_b32 v4, v91 offset:792
	ds_write_b32 v4, v92 offset:1056
	ds_write_b32 v4, v93 offset:1320
	ds_write_b32 v4, v94 offset:1584
	ds_write_b32 v4, v95 offset:1848
	ds_write_b32 v4, v96 offset:2112
	ds_write_b32 v4, v97 offset:2376
	ds_write_b32 v4, v98 offset:2640
	ds_write_b32 v4, v99 offset:2904
	ds_write_b32 v4, v100 offset:3168
	ds_write_b32 v4, v101 offset:3432
	ds_write_b32 v4, v102 offset:3696
	ds_write_b32 v4, v103 offset:3960
	ds_write_b32 v4, v104 offset:4224
	ds_write_b32 v4, v105 offset:4488
	ds_write_b32 v4, v106 offset:4752
	ds_write_b32 v4, v107 offset:5016
	ds_write_b32 v4, v108 offset:5280
	ds_write_b32 v4, v109 offset:5544
	ds_write_b32 v4, v110 offset:5808
	ds_write_b32 v4, v111 offset:6072
	ds_write_b32 v4, v112 offset:6336
	ds_write_b32 v4, v113 offset:6600
	ds_write_b32 v4, v114 offset:6864
	ds_write_b32 v4, v115 offset:7128
	ds_write_b32 v4, v116 offset:7392
	ds_write_b32 v4, v117 offset:7656
	ds_write_b32 v4, v118 offset:7920
	ds_write_b32 v4, v119 offset:8184
	s_waitcnt lgkmcnt(0)
	ds_read_b32 v48, v7
	ds_read_b32 v49, v7 offset:132
	ds_read_b32 v50, v7 offset:264
	ds_read_b32 v51, v7 offset:396
	ds_read_b32 v52, v7 offset:528
	ds_read_b32 v53, v7 offset:660
	ds_read_b32 v54, v7 offset:792
	ds_read_b32 v55, v7 offset:924
	ds_read_b32 v56, v7 offset:32
	ds_read_b32 v57, v7 offset:164
	ds_read_b32 v58, v7 offset:296
	ds_read_b32 v59, v7 offset:428
	ds_read_b32 v60, v7 offset:560
	ds_read_b32 v61, v7 offset:692
	ds_read_b32 v62, v7 offset:824
	ds_read_b32 v63, v7 offset:956
	ds_read_b32 v64, v7 offset:64
	ds_read_b32 v65, v7 offset:196
	ds_read_b32 v66, v7 offset:328
	ds_read_b32 v67, v7 offset:460
	ds_read_b32 v68, v7 offset:592
	ds_read_b32 v69, v7 offset:724
	ds_read_b32 v70, v7 offset:856
	ds_read_b32 v71, v7 offset:988
	ds_read_b32 v72, v7 offset:96
	ds_read_b32 v73, v7 offset:228
	ds_read_b32 v74, v7 offset:360
	ds_read_b32 v75, v7 offset:492
	ds_read_b32 v76, v7 offset:624
	ds_read_b32 v77, v7 offset:756
	ds_read_b32 v78, v7 offset:888
	ds_read_b32 v79, v7 offset:1020
	s_waitcnt lgkmcnt(0)
	v_cvt_pk_bf16_f32 v48, v48, v49
	v_cvt_pk_bf16_f32 v49, v50, v51
	v_cvt_pk_bf16_f32 v50, v52, v53
	v_cvt_pk_bf16_f32 v51, v54, v55
	global_store_dwordx4 v8, v[48:51], s[24:25]
	v_cvt_pk_bf16_f32 v56, v56, v57
	v_cvt_pk_bf16_f32 v57, v58, v59
	v_cvt_pk_bf16_f32 v58, v60, v61
	v_cvt_pk_bf16_f32 v59, v62, v63
	global_store_dwordx4 v9, v[56:59], s[24:25]
	v_cvt_pk_bf16_f32 v64, v64, v65
	v_cvt_pk_bf16_f32 v65, v66, v67
	v_cvt_pk_bf16_f32 v66, v68, v69
	v_cvt_pk_bf16_f32 v67, v70, v71
	global_store_dwordx4 v8, v[64:67], s[24:25] offset:2048
	v_cvt_pk_bf16_f32 v72, v72, v73
	v_cvt_pk_bf16_f32 v73, v74, v75
	v_cvt_pk_bf16_f32 v74, v76, v77
	v_cvt_pk_bf16_f32 v75, v78, v79
	global_store_dwordx4 v9, v[72:75], s[24:25] offset:2048
; #define LAS __attribute__((address_space(3)))
; template <int MAP, bool HASG = false, bool PERMW = false>
; __device__ __forceinline__ void transpose_mat(const float* W, int K, int N, bf16_t* WT, LAS float* scr, int gw, int ngw, int lane, const float* gk = nullptr) {
;     const int nitems = (K / 64) * (N / 32);
;     int it = gw;
;     if (it >= nitems) return;
;     float wv[32];
;     tr_load(W, N, it, lane, wv);
;     for (;;) {
;         __builtin_amdgcn_sched_barrier(0);
; #pragma unroll
;         for (int i = 0; i < 32; ++i) { const int kk = 2 * i + (lane >> 5); scr[kk * 33 + (lane & 31)] = wv[i]; }
;         __builtin_amdgcn_sched_barrier(0);
;         const int nx = it + ngw;
;         if (nx < nitems) tr_load(W, N, nx, lane, wv);
;         __builtin_amdgcn_sched_barrier(0);
;         tr_store<MAP, HASG, PERMW>(K, N, WT, scr, it, lane, gk);
;         if (nx >= nitems) break;
;         it = nx;
;     }
; }
; __global__ void __launch_bounds__(512, 2) mega_fwd(Params p) {
;     ...
;             transpose_mat<3, true, true>(p.in[6] + (size_t)l * D * INW, D, INW, P_W(WS_WIN), scr, gw, ngw, lane, p.in[5] + l * D);
;             transpose_mat<0, false, true>(p.in[7] + (size_t)l * 1024 * D, 1024, D, P_W(WS_WA), scr, gw, ngw, lane);
;             transpose_mat<0, false, true>(p.in[8] + (size_t)l * 2048 * D, 2048, D, P_W(WS_WB), scr, gw, ngw, lane);
;             transpose_mat<0>(p.in[9] + (size_t)l * D * D, D, D, P_W(WS_WO), scr, gw, ngw, lane);
;             transpose_mat<1, true, true>(p.in[11] + (size_t)l * D * DFF, D, DFF, P_W(WS_WGU2), scr, gw, ngw, lane, p.in[10] + l * D);
.Ltc1a_exit:
	v_readlane_b32 s4, v255, 8
	v_readlane_b32 s5, v255, 9
	v_readlane_b32 s20, v255, 6
	v_readlane_b32 s21, v255, 7
	s_nop 3
	s_and_b32 s6, s60, 0x6800000
	s_add_u32 s4, s4, s6
	s_addc_u32 s5, s5, 0
	s_and_b32 s6, s60, 0x2000
	s_add_u32 s20, s20, s6
	s_addc_u32 s21, s21, 0
	s_add_u32 s6, s76, 0x4200000
	s_addc_u32 s7, s77, 0
	s_mov_b32 s9, s18
	s_cmpk_ge_u32 s9, 0x3400
	s_cbranch_scc1 .Ltc1c_exit
	s_mul_hi_u32 s11, s9, 0x4ec4ec4f
	s_lshr_b32 s11, s11, 7
	s_mul_i32 s12, s11, 0x1a0
	s_sub_u32 s12, s9, s12
	s_mul_i32 s13, s11, 0x340000
	s_lshl_b32 s14, s12, 7
	s_add_u32 s13, s13, s14
	s_add_u32 s14, s4, s13
	s_addc_u32 s15, s5, 0
	global_load_dword v16, v12, s[14:15] nt
	s_add_u32 s14, s14, 0x1a000
	s_addc_u32 s15, s15, 0
	global_load_dword v17, v12, s[14:15] nt
	s_add_u32 s14, s14, 0x1a000
	s_addc_u32 s15, s15, 0
	global_load_dword v18, v12, s[14:15] nt
	s_add_u32 s14, s14, 0x1a000
	s_addc_u32 s15, s15, 0
	global_load_dword v19, v12, s[14:15] nt
	s_add_u32 s14, s14, 0x1a000
	s_addc_u32 s15, s15, 0
	global_load_dword v20, v12, s[14:15] nt
	s_add_u32 s14, s14, 0x1a000
	s_addc_u32 s15, s15, 0
	global_load_dword v21, v12, s[14:15] nt
	s_add_u32 s14, s14, 0x1a000
	s_addc_u32 s15, s15, 0
	global_load_dword v22, v12, s[14:15] nt
	s_add_u32 s14, s14, 0x1a000
	s_addc_u32 s15, s15, 0
	global_load_dword v23, v12, s[14:15] nt
	s_add_u32 s14, s14, 0x1a000
	s_addc_u32 s15, s15, 0
	global_load_dword v24, v12, s[14:15] nt
	s_add_u32 s14, s14, 0x1a000
	s_addc_u32 s15, s15, 0
	global_load_dword v25, v12, s[14:15] nt
	s_add_u32 s14, s14, 0x1a000
	s_addc_u32 s15, s15, 0
	global_load_dword v26, v12, s[14:15] nt
	s_add_u32 s14, s14, 0x1a000
	s_addc_u32 s15, s15, 0
	global_load_dword v27, v12, s[14:15] nt
	s_add_u32 s14, s14, 0x1a000
	s_addc_u32 s15, s15, 0
	global_load_dword v28, v12, s[14:15] nt
	s_add_u32 s14, s14, 0x1a000
	s_addc_u32 s15, s15, 0
	global_load_dword v29, v12, s[14:15] nt
	s_add_u32 s14, s14, 0x1a000
	s_addc_u32 s15, s15, 0
	global_load_dword v30, v12, s[14:15] nt
	s_add_u32 s14, s14, 0x1a000
	s_addc_u32 s15, s15, 0
	global_load_dword v31, v12, s[14:15] nt
	s_add_u32 s14, s14, 0x1a000
	s_addc_u32 s15, s15, 0
	global_load_dword v32, v12, s[14:15] nt
	s_add_u32 s14, s14, 0x1a000
	s_addc_u32 s15, s15, 0
	global_load_dword v33, v12, s[14:15] nt
	s_add_u32 s14, s14, 0x1a000
	s_addc_u32 s15, s15, 0
	global_load_dword v34, v12, s[14:15] nt
	s_add_u32 s14, s14, 0x1a000
	s_addc_u32 s15, s15, 0
	global_load_dword v35, v12, s[14:15] nt
	s_add_u32 s14, s14, 0x1a000
	s_addc_u32 s15, s15, 0
	global_load_dword v36, v12, s[14:15] nt
	s_add_u32 s14, s14, 0x1a000
	s_addc_u32 s15, s15, 0
	global_load_dword v37, v12, s[14:15] nt
	s_add_u32 s14, s14, 0x1a000
	s_addc_u32 s15, s15, 0
	global_load_dword v38, v12, s[14:15] nt
	s_add_u32 s14, s14, 0x1a000
	s_addc_u32 s15, s15, 0
	global_load_dword v39, v12, s[14:15] nt
	s_add_u32 s14, s14, 0x1a000
	s_addc_u32 s15, s15, 0
	global_load_dword v40, v12, s[14:15] nt
	s_add_u32 s14, s14, 0x1a000
	s_addc_u32 s15, s15, 0
	global_load_dword v41, v12, s[14:15] nt
	s_add_u32 s14, s14, 0x1a000
	s_addc_u32 s15, s15, 0
	global_load_dword v42, v12, s[14:15] nt
	s_add_u32 s14, s14, 0x1a000
	s_addc_u32 s15, s15, 0
	global_load_dword v43, v12, s[14:15] nt
	s_add_u32 s14, s14, 0x1a000
	s_addc_u32 s15, s15, 0
	global_load_dword v44, v12, s[14:15] nt
	s_add_u32 s14, s14, 0x1a000
	s_addc_u32 s15, s15, 0
	global_load_dword v45, v12, s[14:15] nt
	s_add_u32 s14, s14, 0x1a000
	s_addc_u32 s15, s15, 0
	global_load_dword v46, v12, s[14:15] nt
	s_add_u32 s14, s14, 0x1a000
	s_addc_u32 s15, s15, 0
	global_load_dword v47, v12, s[14:15] nt
	s_lshl_b32 s14, s11, 8
	s_add_u32 s14, s20, s14
	s_addc_u32 s15, s21, 0
	global_load_dwordx4 v[80:83], v14, s[14:15]
	global_load_dwordx4 v[84:87], v14, s[14:15] offset:16
	s_sub_u32 s13, s12, 0x60
	s_cmp_lt_u32 s13, 0x40
	s_cselect_b32 s28, 1, 0
	s_cmp_lt_u32 s12, 0x40
	s_cselect_b32 s13, 1, 0
	s_or_b32 s28, s28, s13
	s_lshr_b32 s16, s12, 2
	s_lshl_b32 s16, s16, 5
	s_add_u32 s16, s16, s11
	s_lshl_b32 s16, s16, 14
	s_and_b32 s13, s12, 1
	s_lshl_b32 s13, s13, 13
	s_bfe_u32 s14, s12, 0x10001
	s_lshl_b32 s14, s14, 11
	s_add_u32 s13, s13, s14
	s_and_b32 s14, s12, 3
	s_lshl_b32 s14, s14, 12
	s_cmp_lg_u32 s28, 0
	s_cselect_b32 s13, s13, s14
	s_add_u32 s16, s16, s13
	s_add_u32 s16, s6, s16
	s_addc_u32 s17, s7, 0
	s_add_u32 s22, s16, 0x1000
	s_addc_u32 s23, s17, 0

; #define LAS __attribute__((address_space(3)))
; __device__ __forceinline__ unsigned pk2(float lo, float hi) { f32x2 f = {lo, hi}; bf16x2_t b = __builtin_convertvector(f, bf16x2_t); return __builtin_bit_cast(unsigned, b); }
; template <int MAP, bool HASG, bool PERMW>
; __device__ __forceinline__ void tr_store(int K, int N, bf16_t* WT, LAS float* scr, int item, int lane, const float* gk) {
;     ...
;     asm volatile("s_waitcnt lgkmcnt(0)" ::: "memory");
;     const int c = lane & 7;
;     f32x4 g0 = {1.f, 1.f, 1.f, 1.f}, g1 = {1.f, 1.f, 1.f, 1.f};
;     if (HASG) { g0 = *(const f32x4*)(gk + k0 + 8 * c); g1 = *(const f32x4*)(gk + k0 + 8 * c + 4); }
; #pragma unroll
;     for (int j = 0; j < 4; ++j) { const int n = (lane >> 3) + 8 * j; const LAS float* s = scr + (8 * c) * 33 + n;
;         u32x4 o; o.x = pk2(s[0 * 33] * g0[0], s[1 * 33] * g0[1]); o.y = pk2(s[2 * 33] * g0[2], s[3 * 33] * g0[3]); o.z = pk2(s[4 * 33] * g1[0], s[5 * 33] * g1[1]); o.w = pk2(s[6 * 33] * g1[2], s[7 * 33] * g1[3]);
;         const int wr_ = rowmap<MAP>(n0 + n), slot_ = PERMW ? ((wr_ & ~31) + invperm32(wr_ & 31)) : wr_;
;         *(u32x4*)((char*)WT + tiled_off(slot_, k0 + 8 * c, K / 64)) = o; }
;     asm volatile("s_waitcnt lgkmcnt(0)" ::: "memory");
; }
.Ltc3e_lastB:
	s_waitcnt vmcnt(0)
	ds_write_b32 v4, v88
	ds_write_b32 v4, v89 offset:264
	ds_write_b32 v4, v90 offset:528
	ds_write_b32 v4, v91 offset:792
	ds_write_b32 v4, v92 offset:1056
	ds_write_b32 v4, v93 offset:1320
	ds_write_b32 v4, v94 offset:1584
	ds_write_b32 v4, v95 offset:1848
	ds_write_b32 v4, v96 offset:2112
	ds_write_b32 v4, v97 offset:2376
	ds_write_b32 v4, v98 offset:2640
	ds_write_b32 v4, v99 offset:2904
	ds_write_b32 v4, v100 offset:3168
	ds_write_b32 v4, v101 offset:3432
	ds_write_b32 v4, v102 offset:3696
	ds_write_b32 v4, v103 offset:3960
	ds_write_b32 v4, v104 offset:4224
	ds_write_b32 v4, v105 offset:4488
	ds_write_b32 v4, v106 offset:4752
	ds_write_b32 v4, v107 offset:5016
	ds_write_b32 v4, v108 offset:5280
	ds_write_b32 v4, v109 offset:5544
	ds_write_b32 v4, v110 offset:5808
	ds_write_b32 v4, v111 offset:6072
	ds_write_b32 v4, v112 offset:6336
	ds_write_b32 v4, v113 offset:6600
	ds_write_b32 v4, v114 offset:6864
	ds_write_b32 v4, v115 offset:7128
	ds_write_b32 v4, v116 offset:7392
	ds_write_b32 v4, v117 offset:7656
	ds_write_b32 v4, v118 offset:7920
	ds_write_b32 v4, v119 offset:8184
	s_waitcnt lgkmcnt(0)
	ds_read_b32 v48, v7
	ds_read_b32 v49, v7 offset:132
	ds_read_b32 v50, v7 offset:264
	ds_read_b32 v51, v7 offset:396
	ds_read_b32 v52, v7 offset:528
	ds_read_b32 v53, v7 offset:660
	ds_read_b32 v54, v7 offset:792
	ds_read_b32 v55, v7 offset:924
	ds_read_b32 v56, v7 offset:32
	ds_read_b32 v57, v7 offset:164
	ds_read_b32 v58, v7 offset:296
	ds_read_b32 v59, v7 offset:428
	ds_read_b32 v60, v7 offset:560
	ds_read_b32 v61, v7 offset:692
	ds_read_b32 v62, v7 offset:824
	ds_read_b32 v63, v7 offset:956
	ds_read_b32 v64, v7 offset:64
	ds_read_b32 v65, v7 offset:196
	ds_read_b32 v66, v7 offset:328
	ds_read_b32 v67, v7 offset:460
	ds_read_b32 v68, v7 offset:592
	ds_read_b32 v69, v7 offset:724
	ds_read_b32 v70, v7 offset:856
	ds_read_b32 v71, v7 offset:988
	ds_read_b32 v72, v7 offset:96
	ds_read_b32 v73, v7 offset:228
	ds_read_b32 v74, v7 offset:360
	ds_read_b32 v75, v7 offset:492
	ds_read_b32 v76, v7 offset:624
	ds_read_b32 v77, v7 offset:756
	ds_read_b32 v78, v7 offset:888
	ds_read_b32 v79, v7 offset:1020
	s_waitcnt lgkmcnt(0)
	v_mul_f32_e32 v48, v48, v120
	v_mul_f32_e32 v49, v49, v121
	v_mul_f32_e32 v50, v50, v122
	v_mul_f32_e32 v51, v51, v123
	v_mul_f32_e32 v52, v52, v124
	v_mul_f32_e32 v53, v53, v125
	v_mul_f32_e32 v54, v54, v126
	v_mul_f32_e32 v55, v55, v127
	v_cvt_pk_bf16_f32 v48, v48, v49
	v_cvt_pk_bf16_f32 v49, v50, v51
	v_cvt_pk_bf16_f32 v50, v52, v53
	v_cvt_pk_bf16_f32 v51, v54, v55
	global_store_dwordx4 v10, v[48:51], s[24:25]
	v_mul_f32_e32 v56, v56, v120
	v_mul_f32_e32 v57, v57, v121
	v_mul_f32_e32 v58, v58, v122
	v_mul_f32_e32 v59, v59, v123
	v_mul_f32_e32 v60, v60, v124
	v_mul_f32_e32 v61, v61, v125
	v_mul_f32_e32 v62, v62, v126
	v_mul_f32_e32 v63, v63, v127
	v_cvt_pk_bf16_f32 v56, v56, v57
	v_cvt_pk_bf16_f32 v57, v58, v59
	v_cvt_pk_bf16_f32 v58, v60, v61
	v_cvt_pk_bf16_f32 v59, v62, v63
	global_store_dwordx4 v10, v[56:59], s[24:25] offset:256
	v_mul_f32_e32 v64, v64, v120
	v_mul_f32_e32 v65, v65, v121
	v_mul_f32_e32 v66, v66, v122
	v_mul_f32_e32 v67, v67, v123
	v_mul_f32_e32 v68, v68, v124
	v_mul_f32_e32 v69, v69, v125
	v_mul_f32_e32 v70, v70, v126
	v_mul_f32_e32 v71, v71, v127
	v_cvt_pk_bf16_f32 v64, v64, v65
	v_cvt_pk_bf16_f32 v65, v66, v67
	v_cvt_pk_bf16_f32 v66, v68, v69
	v_cvt_pk_bf16_f32 v67, v70, v71
	global_store_dwordx4 v11, v[64:67], s[24:25] offset:512
	v_mul_f32_e32 v72, v72, v120
	v_mul_f32_e32 v73, v73, v121
	v_mul_f32_e32 v74, v74, v122
	v_mul_f32_e32 v75, v75, v123
	v_mul_f32_e32 v76, v76, v124
	v_mul_f32_e32 v77, v77, v125
	v_mul_f32_e32 v78, v78, v126
	v_mul_f32_e32 v79, v79, v127
	v_cvt_pk_bf16_f32 v72, v72, v73
	v_cvt_pk_bf16_f32 v73, v74, v75
	v_cvt_pk_bf16_f32 v74, v76, v77
	v_cvt_pk_bf16_f32 v75, v78, v79
	global_store_dwordx4 v11, v[72:75], s[24:25] offset:768
; #define LAS __attribute__((address_space(3)))
; template <int MAP, bool HASG = false, bool PERMW = false>
; __device__ __forceinline__ void transpose_mat(const float* W, int K, int N, bf16_t* WT, LAS float* scr, int gw, int ngw, int lane, const float* gk = nullptr) {
;     const int nitems = (K / 64) * (N / 32);
;     int it = gw;
;     if (it >= nitems) return;
;     float wv[32];
;     tr_load(W, N, it, lane, wv);
;     for (;;) {
;         __builtin_amdgcn_sched_barrier(0);
; #pragma unroll
;         for (int i = 0; i < 32; ++i) { const int kk = 2 * i + (lane >> 5); scr[kk * 33 + (lane & 31)] = wv[i]; }
;         __builtin_amdgcn_sched_barrier(0);
;         const int nx = it + ngw;
;         if (nx < nitems) tr_load(W, N, nx, lane, wv);
.Ltc3e_exit:
	v_readlane_b32 s4, v254, 8
	v_readlane_b32 s5, v254, 9
	v_readlane_b32 s20, v254, 4
	v_readlane_b32 s21, v254, 5
	s_nop 3
	s_and_b32 s6, s60, 0x2c00000
	s_add_u32 s4, s4, s6
	s_addc_u32 s5, s5, 0
	s_and_b32 s6, s60, 0x2000
	s_add_u32 s20, s20, s6
	s_addc_u32 s21, s21, 0
	s_add_u32 s6, s76, 0x8a00000
	s_addc_u32 s7, s77, 0
	s_mov_b32 s9, s18
	s_cmpk_ge_u32 s9, 0x1600
	s_cbranch_scc1 .Ltc3d_exit
	s_mul_hi_u32 s11, s9, 0x2e8ba2e9
	s_lshr_b32 s11, s11, 5
	s_mul_i32 s12, s11, 0xb0
	s_sub_u32 s12, s9, s12
	s_mul_i32 s13, s11, 0x160000
	s_lshl_b32 s14, s12, 7
	s_add_u32 s13, s13, s14
	s_add_u32 s14, s4, s13
	s_addc_u32 s15, s5, 0
	global_load_dword v16, v15, s[14:15] nt
	s_add_u32 s14, s14, 0xb000
	s_addc_u32 s15, s15, 0
	global_load_dword v17, v15, s[14:15] nt
	s_add_u32 s14, s14, 0xb000
	s_addc_u32 s15, s15, 0
	global_load_dword v18, v15, s[14:15] nt
	s_add_u32 s14, s14, 0xb000
	s_addc_u32 s15, s15, 0
	global_load_dword v19, v15, s[14:15] nt
	s_add_u32 s14, s14, 0xb000
	s_addc_u32 s15, s15, 0
	global_load_dword v20, v15, s[14:15] nt
	s_add_u32 s14, s14, 0xb000
	s_addc_u32 s15, s15, 0
	global_load_dword v21, v15, s[14:15] nt
	s_add_u32 s14, s14, 0xb000
	s_addc_u32 s15, s15, 0
	global_load_dword v22, v15, s[14:15] nt
	s_add_u32 s14, s14, 0xb000
	s_addc_u32 s15, s15, 0
	global_load_dword v23, v15, s[14:15] nt
	s_add_u32 s14, s14, 0xb000
	s_addc_u32 s15, s15, 0
	global_load_dword v24, v15, s[14:15] nt
	s_add_u32 s14, s14, 0xb000
	s_addc_u32 s15, s15, 0
	global_load_dword v25, v15, s[14:15] nt
	s_add_u32 s14, s14, 0xb000
	s_addc_u32 s15, s15, 0
	global_load_dword v26, v15, s[14:15] nt
	s_add_u32 s14, s14, 0xb000
	s_addc_u32 s15, s15, 0
	global_load_dword v27, v15, s[14:15] nt
	s_add_u32 s14, s14, 0xb000
	s_addc_u32 s15, s15, 0
	global_load_dword v28, v15, s[14:15] nt
	s_add_u32 s14, s14, 0xb000
	s_addc_u32 s15, s15, 0
	global_load_dword v29, v15, s[14:15] nt
	s_add_u32 s14, s14, 0xb000
	s_addc_u32 s15, s15, 0
	global_load_dword v30, v15, s[14:15] nt
	s_add_u32 s14, s14, 0xb000
	s_addc_u32 s15, s15, 0
	global_load_dword v31, v15, s[14:15] nt
	s_add_u32 s14, s14, 0xb000
	s_addc_u32 s15, s15, 0
	global_load_dword v32, v15, s[14:15] nt
	s_add_u32 s14, s14, 0xb000
	s_addc_u32 s15, s15, 0
	global_load_dword v33, v15, s[14:15] nt
	s_add_u32 s14, s14, 0xb000
	s_addc_u32 s15, s15, 0
	global_load_dword v34, v15, s[14:15] nt
	s_add_u32 s14, s14, 0xb000
	s_addc_u32 s15, s15, 0
	global_load_dword v35, v15, s[14:15] nt
	s_add_u32 s14, s14, 0xb000
	s_addc_u32 s15, s15, 0
	global_load_dword v36, v15, s[14:15] nt
	s_add_u32 s14, s14, 0xb000
	s_addc_u32 s15, s15, 0
	global_load_dword v37, v15, s[14:15] nt
	s_add_u32 s14, s14, 0xb000
	s_addc_u32 s15, s15, 0
	global_load_dword v38, v15, s[14:15] nt
	s_add_u32 s14, s14, 0xb000
	s_addc_u32 s15, s15, 0
	global_load_dword v39, v15, s[14:15] nt
	s_add_u32 s14, s14, 0xb000
	s_addc_u32 s15, s15, 0
	global_load_dword v40, v15, s[14:15] nt
	s_add_u32 s14, s14, 0xb000
	s_addc_u32 s15, s15, 0
	global_load_dword v41, v15, s[14:15] nt
	s_add_u32 s14, s14, 0xb000
	s_addc_u32 s15, s15, 0
	global_load_dword v42, v15, s[14:15] nt
	s_add_u32 s14, s14, 0xb000
	s_addc_u32 s15, s15, 0
	global_load_dword v43, v15, s[14:15] nt
	s_add_u32 s14, s14, 0xb000
	s_addc_u32 s15, s15, 0
	global_load_dword v44, v15, s[14:15] nt
	s_add_u32 s14, s14, 0xb000
	s_addc_u32 s15, s15, 0
	global_load_dword v45, v15, s[14:15] nt
	s_add_u32 s14, s14, 0xb000
	s_addc_u32 s15, s15, 0
	global_load_dword v46, v15, s[14:15] nt
	s_add_u32 s14, s14, 0xb000
	s_addc_u32 s15, s15, 0
	global_load_dword v47, v15, s[14:15] nt
	s_lshl_b32 s14, s11, 8
	s_add_u32 s14, s20, s14
	s_addc_u32 s15, s21, 0
	global_load_dwordx4 v[80:83], v14, s[14:15]
	global_load_dwordx4 v[84:87], v14, s[14:15] offset:16
	s_lshr_b32 s16, s12, 2
	s_lshl_b32 s16, s16, 1
	s_add_u32 s16, s16, 1
	s_lshl_b32 s16, s16, 5
	s_add_u32 s16, s16, s11
	s_lshl_b32 s16, s16, 14
	s_and_b32 s17, s12, 3
	s_lshl_b32 s17, s17, 12
	s_add_u32 s16, s16, s17
	s_add_u32 s16, s6, s16
	s_addc_u32 s17, s7, 0
